# B/C conv prompt item rewritten by hand: only halo rows waited before the barrier, own rows streamed (packed f32 FMA taps, SiLU, bf16 pack, store)
# baseline (speedup 1.0000x reference)
; __device__ __forceinline__ unsigned pk2(float lo, float hi) { unsigned r; asm("v_cvt_pk_bf16_f32 %0, %1, %2" : "=v"(r) : "v"(lo), "v"(hi)); return r; }
; __device__ __forceinline__ void convbc_item(const Args& a, int layer, bool is_sample, int b, int cg32, int seq_row0, bf16_t* proj, const int tid) {
;     const int oc = is_sample ? (tid & 15) : (tid & 3), ts = is_sample ? (tid >> 4) : (tid >> 2);
;     const int L = is_sample ? DSEQ : SEQ, seglen = is_sample ? 2 : 16;
;     const bool act = true;
;     const int ch = DIN + (is_sample ? cg32 * 128 : cg32 * 32) + oc * 8;
;     const int t0 = ts * seglen;
;     u32x4 rw[19];
;     float cw[4][8], cb[8];
;     if (act) {
;         const float* wp = a.in[14] + (size_t)layer * 4 * CONVC + ch; const float* bp = a.in[15] + (size_t)layer * CONVC + ch;
; #pragma unroll
;         for (int k = 0; k < 4; ++k) { const f32x4 w0 = *(const f32x4*)(wp + k * CONVC), w1 = *(const f32x4*)(wp + k * CONVC + 4);
;             cw[k][0] = w0[0]; cw[k][1] = w0[1]; cw[k][2] = w0[2]; cw[k][3] = w0[3]; cw[k][4] = w1[0]; cw[k][5] = w1[1]; cw[k][6] = w1[2]; cw[k][7] = w1[3]; }
;         const f32x4 b0 = *(const f32x4*)bp, b1 = *(const f32x4*)(bp + 4);
;         cb[0] = b0[0]; cb[1] = b0[1]; cb[2] = b0[2]; cb[3] = b0[3]; cb[4] = b1[0]; cb[5] = b1[1]; cb[6] = b1[2]; cb[7] = b1[3];
; #pragma unroll
;         for (int r = 0; r < 19; ++r) {
;             const int tt = t0 - 3 + r;
;             if (r < 3 + seglen) {
;                 if (tt >= 0) rw[r] = *(const u32x4*)(proj + (size_t)(seq_row0 + tt) * PN + C_XBC + ch);
;                 else if (is_sample) { const float* pp = a.in[4] + ((size_t)(layer * NSB + b) * 3 + (3 + tt)) * CONVC + ch;
;                     const f32x4 p0 = *(const f32x4*)pp, p1 = *(const f32x4*)(pp + 4);
;                     rw[r].x = pk2(p0[0], p0[1]); rw[r].y = pk2(p0[2], p0[3]); rw[r].z = pk2(p1[0], p1[1]); rw[r].w = pk2(p1[2], p1[3]); }
;                 else rw[r] = (u32x4){0u, 0u, 0u, 0u};
;             }
;         }
;     }
;     __syncthreads();
.LBB0_294:
	s_and_b32 s4, s21, 31
	s_lshr_b32 s5, s21, 5
	s_mul_i32 s8, s5, 0x2300000
	s_lshl_b32 s9, s4, 6
	s_add_i32 s9, s9, 0x2000
	s_add_u32 s42, s18, s8
	s_addc_u32 s43, s19, 0
	s_add_u32 s42, s42, s9
	s_addc_u32 s43, s43, 0
	s_sub_u32 s44, s42, 0xd200
	s_subb_u32 s45, s43, 0
	s_mov_b32 s48, s42
	s_mov_b32 s49, s43
	v_and_b32_e32 v3, 3, v166
	v_lshrrev_b32_e32 v2, 2, v166
	v_mul_u32_u24_e32 v2, 0x46000, v2
	v_lshl_add_u32 v2, v3, 4, v2
	v_lshlrev_b32_e32 v3, 5, v3
	v_readlane_b32 s50, v255, 9
	v_readlane_b32 s51, v255, 10
	v_readlane_b32 s52, v255, 11
	v_readlane_b32 s53, v255, 12
	s_lshl_b32 s9, s4, 7
	s_add_i32 s9, s9, 0x2000
	s_add_u32 s50, s50, s9
	s_addc_u32 s51, s51, 0
	s_add_u32 s52, s52, s9
	s_addc_u32 s53, s53, 0
	global_load_dwordx4 v[4:7], v3, s[50:51]
	global_load_dwordx4 v[8:11], v3, s[50:51] offset:16
	s_add_u32 s50, s50, 0x3000
	s_addc_u32 s51, s51, 0
	global_load_dwordx4 v[12:15], v3, s[50:51]
	global_load_dwordx4 v[16:19], v3, s[50:51] offset:16
	s_add_u32 s50, s50, 0x3000
	s_addc_u32 s51, s51, 0
	global_load_dwordx4 v[20:23], v3, s[50:51]
	global_load_dwordx4 v[24:27], v3, s[50:51] offset:16
	s_add_u32 s50, s50, 0x3000
	s_addc_u32 s51, s51, 0
	global_load_dwordx4 v[28:31], v3, s[50:51]
	global_load_dwordx4 v[32:35], v3, s[50:51] offset:16
	global_load_dwordx4 v[36:39], v3, s[52:53]
	global_load_dwordx4 v[40:43], v3, s[52:53] offset:16
	v_mov_b32_e32 v44, 0
	v_mov_b32_e32 v45, 0
	v_mov_b32_e32 v46, 0
	v_mov_b32_e32 v47, 0
	v_mov_b32_e32 v48, 0
	v_mov_b32_e32 v49, 0
	v_mov_b32_e32 v50, 0
	v_mov_b32_e32 v51, 0
	v_mov_b32_e32 v52, 0
	v_mov_b32_e32 v53, 0
	v_mov_b32_e32 v54, 0
	v_mov_b32_e32 v55, 0
	v_cmp_lt_u32_e32 vcc, 3, v166
	s_and_saveexec_b64 s[54:55], vcc
	global_load_dwordx4 v[44:47], v2, s[44:45]
	s_add_u32 s44, s44, 0x4600
	s_addc_u32 s45, s45, 0
	global_load_dwordx4 v[48:51], v2, s[44:45]
	s_add_u32 s44, s44, 0x4600
	s_addc_u32 s45, s45, 0
	global_load_dwordx4 v[52:55], v2, s[44:45]
	s_add_u32 s44, s44, 0x4600
	s_addc_u32 s45, s45, 0
	s_mov_b64 exec, s[54:55]
	global_load_dwordx4 v[56:59], v2, s[44:45]
	s_add_u32 s44, s44, 0x4600
	s_addc_u32 s45, s45, 0
	global_load_dwordx4 v[60:63], v2, s[44:45]
	s_add_u32 s44, s44, 0x4600
	s_addc_u32 s45, s45, 0
	global_load_dwordx4 v[64:67], v2, s[44:45]
	s_add_u32 s44, s44, 0x4600
	s_addc_u32 s45, s45, 0
	global_load_dwordx4 v[68:71], v2, s[44:45]
	s_add_u32 s44, s44, 0x4600
	s_addc_u32 s45, s45, 0
	global_load_dwordx4 v[72:75], v2, s[44:45]
	s_add_u32 s44, s44, 0x4600
	s_addc_u32 s45, s45, 0
	global_load_dwordx4 v[76:79], v2, s[44:45]
	s_add_u32 s44, s44, 0x4600
	s_addc_u32 s45, s45, 0
	global_load_dwordx4 v[80:83], v2, s[44:45]
	s_add_u32 s44, s44, 0x4600
	s_addc_u32 s45, s45, 0
	global_load_dwordx4 v[88:91], v2, s[44:45]
	s_add_u32 s44, s44, 0x4600
	s_addc_u32 s45, s45, 0
	global_load_dwordx4 v[92:95], v2, s[44:45]
	s_add_u32 s44, s44, 0x4600
	s_addc_u32 s45, s45, 0
	global_load_dwordx4 v[96:99], v2, s[44:45]
	s_add_u32 s44, s44, 0x4600
	s_addc_u32 s45, s45, 0
	global_load_dwordx4 v[104:107], v2, s[44:45]
	s_add_u32 s44, s44, 0x4600
	s_addc_u32 s45, s45, 0
	global_load_dwordx4 v[108:111], v2, s[44:45]
	s_add_u32 s44, s44, 0x4600
	s_addc_u32 s45, s45, 0
	global_load_dwordx4 v[112:115], v2, s[44:45]
	s_add_u32 s44, s44, 0x4600
	s_addc_u32 s45, s45, 0
	global_load_dwordx4 v[116:119], v2, s[44:45]
	s_add_u32 s44, s44, 0x4600
	s_addc_u32 s45, s45, 0
	global_load_dwordx4 v[184:187], v2, s[44:45]
	s_add_u32 s44, s44, 0x4600
	s_addc_u32 s45, s45, 0
	global_load_dwordx4 v[188:191], v2, s[44:45]
	s_waitcnt vmcnt(16)
	s_barrier
	v_lshlrev_b32_e32 v120, 16, v44
	v_and_b32_e32 v121, 0xffff0000, v44
	v_lshlrev_b32_e32 v122, 16, v45
	v_and_b32_e32 v123, 0xffff0000, v45
	v_lshlrev_b32_e32 v124, 16, v46
	v_and_b32_e32 v125, 0xffff0000, v46
	v_lshlrev_b32_e32 v126, 16, v47
	v_and_b32_e32 v127, 0xffff0000, v47
	v_lshlrev_b32_e32 v128, 16, v48
	v_and_b32_e32 v129, 0xffff0000, v48
	v_lshlrev_b32_e32 v130, 16, v49
	v_and_b32_e32 v131, 0xffff0000, v49
	v_lshlrev_b32_e32 v132, 16, v50
	v_and_b32_e32 v133, 0xffff0000, v50
	v_lshlrev_b32_e32 v134, 16, v51
	v_and_b32_e32 v135, 0xffff0000, v51
	v_lshlrev_b32_e32 v136, 16, v52
	v_and_b32_e32 v137, 0xffff0000, v52
	v_lshlrev_b32_e32 v138, 16, v53
	v_and_b32_e32 v139, 0xffff0000, v53
	v_lshlrev_b32_e32 v140, 16, v54
	v_and_b32_e32 v141, 0xffff0000, v54
	v_lshlrev_b32_e32 v142, 16, v55
	v_and_b32_e32 v143, 0xffff0000, v55
	v_readlane_b32 s9, v255, 31
	s_cmp_lg_u32 s9, 0
	s_cselect_b32 s9, 8, 0
	s_add_i32 s5, s5, s9
	v_readlane_b32 s9, v255, 5
	s_lshr_b32 s9, s9, 12
	s_lshl_b32 s9, s9, 4
	s_add_i32 s5, s5, s9
	s_mul_i32 s5, s5, 0x9000
	s_lshl_b32 s9, s4, 7
	s_add_i32 s9, s9, 0x2000
	s_add_u32 s52, s24, 0x8800000
	s_addc_u32 s53, s25, 0
	s_add_u32 s52, s52, s5
	s_addc_u32 s53, s53, 0
	s_add_u32 s52, s52, s9
	s_addc_u32 s53, s53, 0
	s_waitcnt vmcnt(15)
; __device__ __forceinline__ unsigned pk2(float lo, float hi) { unsigned r; asm("v_cvt_pk_bf16_f32 %0, %1, %2" : "=v"(r) : "v"(lo), "v"(hi)); return r; }
; __device__ __forceinline__ float bflo(unsigned w) { return __uint_as_float(w << 16); }
; __device__ __forceinline__ float bfhi(unsigned w) { return __uint_as_float(w & 0xffff0000u); }
; __device__ __forceinline__ float siluf_(float x) { return x * __builtin_amdgcn_rcpf(1.f + __expf(-x)); }
; __device__ __forceinline__ void convbc_item(const Args& a, int layer, bool is_sample, int b, int cg32, int seq_row0, bf16_t* proj, const int tid) {
;     ...
;         for (int t = 0; t < 16; ++t) {
;             if (t < seglen) {
;                 float o[8];
; #pragma unroll
;                 for (int i = 0; i < 8; ++i) o[i] = cb[i];
; #pragma unroll
;                 for (int k = 0; k < 4; ++k) { const u32x4 w = rw[t + k];
;                     o[0] += cw[k][0] * bflo(w.x); o[1] += cw[k][1] * bfhi(w.x); o[2] += cw[k][2] * bflo(w.y); o[3] += cw[k][3] * bfhi(w.y);
;                     o[4] += cw[k][4] * bflo(w.z); o[5] += cw[k][5] * bfhi(w.z); o[6] += cw[k][6] * bflo(w.w); o[7] += cw[k][7] * bfhi(w.w); }
;                 u32x4 w; w.x = pk2(siluf_(o[0]), siluf_(o[1])); w.y = pk2(siluf_(o[2]), siluf_(o[3])); w.z = pk2(siluf_(o[4]), siluf_(o[5])); w.w = pk2(siluf_(o[6]), siluf_(o[7]));
;                 *(u32x4*)(proj + (size_t)(seq_row0 + t0 + t) * PN + C_XBC + ch) = w;
	v_lshlrev_b32_e32 v144, 16, v56
	v_and_b32_e32 v145, 0xffff0000, v56
	v_lshlrev_b32_e32 v146, 16, v57
	v_and_b32_e32 v147, 0xffff0000, v57
	v_lshlrev_b32_e32 v148, 16, v58
	v_and_b32_e32 v149, 0xffff0000, v58
	v_lshlrev_b32_e32 v150, 16, v59
	v_and_b32_e32 v151, 0xffff0000, v59
	v_pk_fma_f32 v[152:153], v[4:5], v[120:121], v[36:37]
	v_pk_fma_f32 v[154:155], v[6:7], v[122:123], v[38:39]
	v_pk_fma_f32 v[156:157], v[8:9], v[124:125], v[40:41]
	v_pk_fma_f32 v[158:159], v[10:11], v[126:127], v[42:43]
	v_pk_fma_f32 v[152:153], v[12:13], v[128:129], v[152:153]
	v_pk_fma_f32 v[154:155], v[14:15], v[130:131], v[154:155]
	v_pk_fma_f32 v[156:157], v[16:17], v[132:133], v[156:157]
	v_pk_fma_f32 v[158:159], v[18:19], v[134:135], v[158:159]
	v_pk_fma_f32 v[152:153], v[20:21], v[136:137], v[152:153]
	v_pk_fma_f32 v[154:155], v[22:23], v[138:139], v[154:155]
	v_pk_fma_f32 v[156:157], v[24:25], v[140:141], v[156:157]
	v_pk_fma_f32 v[158:159], v[26:27], v[142:143], v[158:159]
	v_pk_fma_f32 v[152:153], v[28:29], v[144:145], v[152:153]
	v_pk_fma_f32 v[154:155], v[30:31], v[146:147], v[154:155]
	v_pk_fma_f32 v[156:157], v[32:33], v[148:149], v[156:157]
	v_pk_fma_f32 v[158:159], v[34:35], v[150:151], v[158:159]
	v_mul_f32_e32 v176, 0xbfb8aa3b, v152
	v_mul_f32_e32 v177, 0xbfb8aa3b, v153
	v_mul_f32_e32 v178, 0xbfb8aa3b, v154
	v_mul_f32_e32 v179, 0xbfb8aa3b, v155
	v_mul_f32_e32 v180, 0xbfb8aa3b, v156
	v_mul_f32_e32 v181, 0xbfb8aa3b, v157
	v_mul_f32_e32 v182, 0xbfb8aa3b, v158
	v_mul_f32_e32 v183, 0xbfb8aa3b, v159
	v_exp_f32_e32 v176, v176
	v_exp_f32_e32 v177, v177
	v_exp_f32_e32 v178, v178
	v_exp_f32_e32 v179, v179
	v_exp_f32_e32 v180, v180
	v_exp_f32_e32 v181, v181
	v_exp_f32_e32 v182, v182
	v_exp_f32_e32 v183, v183
	v_pk_add_f32 v[176:177], v[176:177], 1.0 op_sel_hi:[1,0]
	v_pk_add_f32 v[178:179], v[178:179], 1.0 op_sel_hi:[1,0]
	v_pk_add_f32 v[180:181], v[180:181], 1.0 op_sel_hi:[1,0]
	v_pk_add_f32 v[182:183], v[182:183], 1.0 op_sel_hi:[1,0]
	v_rcp_f32_e32 v176, v176
	v_rcp_f32_e32 v177, v177
	v_rcp_f32_e32 v178, v178
	v_rcp_f32_e32 v179, v179
	v_rcp_f32_e32 v180, v180
	v_rcp_f32_e32 v181, v181
	v_rcp_f32_e32 v182, v182
	v_rcp_f32_e32 v183, v183
	v_pk_mul_f32 v[152:153], v[152:153], v[176:177]
	v_pk_mul_f32 v[154:155], v[154:155], v[178:179]
	v_pk_mul_f32 v[156:157], v[156:157], v[180:181]
	v_pk_mul_f32 v[158:159], v[158:159], v[182:183]
	v_cvt_pk_bf16_f32 v176, v152, v153
	v_cvt_pk_bf16_f32 v177, v154, v155
	v_cvt_pk_bf16_f32 v178, v156, v157
	v_cvt_pk_bf16_f32 v179, v158, v159
	global_store_dwordx4 v2, v[176:179], s[48:49]
	s_add_u32 s48, s48, 0x4600
	s_addc_u32 s49, s49, 0
	s_waitcnt vmcnt(15)
	v_lshlrev_b32_e32 v120, 16, v60
	v_and_b32_e32 v121, 0xffff0000, v60
	v_lshlrev_b32_e32 v122, 16, v61
	v_and_b32_e32 v123, 0xffff0000, v61
	v_lshlrev_b32_e32 v124, 16, v62
	v_and_b32_e32 v125, 0xffff0000, v62
	v_lshlrev_b32_e32 v126, 16, v63
	v_and_b32_e32 v127, 0xffff0000, v63
	v_pk_fma_f32 v[152:153], v[4:5], v[128:129], v[36:37]
	v_pk_fma_f32 v[154:155], v[6:7], v[130:131], v[38:39]
	v_pk_fma_f32 v[156:157], v[8:9], v[132:133], v[40:41]
	v_pk_fma_f32 v[158:159], v[10:11], v[134:135], v[42:43]
	v_pk_fma_f32 v[152:153], v[12:13], v[136:137], v[152:153]
	v_pk_fma_f32 v[154:155], v[14:15], v[138:139], v[154:155]
	v_pk_fma_f32 v[156:157], v[16:17], v[140:141], v[156:157]
	v_pk_fma_f32 v[158:159], v[18:19], v[142:143], v[158:159]
	v_pk_fma_f32 v[152:153], v[20:21], v[144:145], v[152:153]
	v_pk_fma_f32 v[154:155], v[22:23], v[146:147], v[154:155]
	v_pk_fma_f32 v[156:157], v[24:25], v[148:149], v[156:157]
	v_pk_fma_f32 v[158:159], v[26:27], v[150:151], v[158:159]
	v_pk_fma_f32 v[152:153], v[28:29], v[120:121], v[152:153]
	v_pk_fma_f32 v[154:155], v[30:31], v[122:123], v[154:155]
	v_pk_fma_f32 v[156:157], v[32:33], v[124:125], v[156:157]
	v_pk_fma_f32 v[158:159], v[34:35], v[126:127], v[158:159]
	v_mul_f32_e32 v176, 0xbfb8aa3b, v152
	v_mul_f32_e32 v177, 0xbfb8aa3b, v153
	v_mul_f32_e32 v178, 0xbfb8aa3b, v154
	v_mul_f32_e32 v179, 0xbfb8aa3b, v155
	v_mul_f32_e32 v180, 0xbfb8aa3b, v156
	v_mul_f32_e32 v181, 0xbfb8aa3b, v157
	v_mul_f32_e32 v182, 0xbfb8aa3b, v158
	v_mul_f32_e32 v183, 0xbfb8aa3b, v159
	v_exp_f32_e32 v176, v176
	v_exp_f32_e32 v177, v177
	v_exp_f32_e32 v178, v178
	v_exp_f32_e32 v179, v179
	v_exp_f32_e32 v180, v180
	v_exp_f32_e32 v181, v181
	v_exp_f32_e32 v182, v182
	v_exp_f32_e32 v183, v183
	v_pk_add_f32 v[176:177], v[176:177], 1.0 op_sel_hi:[1,0]
	v_pk_add_f32 v[178:179], v[178:179], 1.0 op_sel_hi:[1,0]
	v_pk_add_f32 v[180:181], v[180:181], 1.0 op_sel_hi:[1,0]
	v_pk_add_f32 v[182:183], v[182:183], 1.0 op_sel_hi:[1,0]
	v_rcp_f32_e32 v176, v176
	v_rcp_f32_e32 v177, v177
	v_rcp_f32_e32 v178, v178
	v_rcp_f32_e32 v179, v179
	v_rcp_f32_e32 v180, v180
	v_rcp_f32_e32 v181, v181
	v_rcp_f32_e32 v182, v182
	v_rcp_f32_e32 v183, v183
	v_pk_mul_f32 v[152:153], v[152:153], v[176:177]
	v_pk_mul_f32 v[154:155], v[154:155], v[178:179]
	v_pk_mul_f32 v[156:157], v[156:157], v[180:181]
	v_pk_mul_f32 v[158:159], v[158:159], v[182:183]
	v_cvt_pk_bf16_f32 v176, v152, v153
	v_cvt_pk_bf16_f32 v177, v154, v155
	v_cvt_pk_bf16_f32 v178, v156, v157
	v_cvt_pk_bf16_f32 v179, v158, v159
	global_store_dwordx4 v2, v[176:179], s[48:49]
	s_add_u32 s48, s48, 0x4600
	s_addc_u32 s49, s49, 0
	s_waitcnt vmcnt(15)
; __device__ __forceinline__ unsigned pk2(float lo, float hi) { unsigned r; asm("v_cvt_pk_bf16_f32 %0, %1, %2" : "=v"(r) : "v"(lo), "v"(hi)); return r; }
; __device__ __forceinline__ float bflo(unsigned w) { return __uint_as_float(w << 16); }
; __device__ __forceinline__ float bfhi(unsigned w) { return __uint_as_float(w & 0xffff0000u); }
; __device__ __forceinline__ float siluf_(float x) { return x * __builtin_amdgcn_rcpf(1.f + __expf(-x)); }
; __device__ __forceinline__ void convbc_item(const Args& a, int layer, bool is_sample, int b, int cg32, int seq_row0, bf16_t* proj, const int tid) {
;     ...
;                 for (int i = 0; i < 8; ++i) o[i] = cb[i];
; #pragma unroll
;                 for (int k = 0; k < 4; ++k) { const u32x4 w = rw[t + k];
;                     o[0] += cw[k][0] * bflo(w.x); o[1] += cw[k][1] * bfhi(w.x); o[2] += cw[k][2] * bflo(w.y); o[3] += cw[k][3] * bfhi(w.y);
;                     o[4] += cw[k][4] * bflo(w.z); o[5] += cw[k][5] * bfhi(w.z); o[6] += cw[k][6] * bflo(w.w); o[7] += cw[k][7] * bfhi(w.w); }
;                 u32x4 w; w.x = pk2(siluf_(o[0]), siluf_(o[1])); w.y = pk2(siluf_(o[2]), siluf_(o[3])); w.z = pk2(siluf_(o[4]), siluf_(o[5])); w.w = pk2(siluf_(o[6]), siluf_(o[7]));
;                 *(u32x4*)(proj + (size_t)(seq_row0 + t0 + t) * PN + C_XBC + ch) = w;
	v_lshlrev_b32_e32 v128, 16, v64
	v_and_b32_e32 v129, 0xffff0000, v64
	v_lshlrev_b32_e32 v130, 16, v65
	v_and_b32_e32 v131, 0xffff0000, v65
	v_lshlrev_b32_e32 v132, 16, v66
	v_and_b32_e32 v133, 0xffff0000, v66
	v_lshlrev_b32_e32 v134, 16, v67
	v_and_b32_e32 v135, 0xffff0000, v67
	v_pk_fma_f32 v[152:153], v[4:5], v[136:137], v[36:37]
	v_pk_fma_f32 v[154:155], v[6:7], v[138:139], v[38:39]
	v_pk_fma_f32 v[156:157], v[8:9], v[140:141], v[40:41]
	v_pk_fma_f32 v[158:159], v[10:11], v[142:143], v[42:43]
	v_pk_fma_f32 v[152:153], v[12:13], v[144:145], v[152:153]
	v_pk_fma_f32 v[154:155], v[14:15], v[146:147], v[154:155]
	v_pk_fma_f32 v[156:157], v[16:17], v[148:149], v[156:157]
	v_pk_fma_f32 v[158:159], v[18:19], v[150:151], v[158:159]
	v_pk_fma_f32 v[152:153], v[20:21], v[120:121], v[152:153]
	v_pk_fma_f32 v[154:155], v[22:23], v[122:123], v[154:155]
	v_pk_fma_f32 v[156:157], v[24:25], v[124:125], v[156:157]
	v_pk_fma_f32 v[158:159], v[26:27], v[126:127], v[158:159]
	v_pk_fma_f32 v[152:153], v[28:29], v[128:129], v[152:153]
	v_pk_fma_f32 v[154:155], v[30:31], v[130:131], v[154:155]
	v_pk_fma_f32 v[156:157], v[32:33], v[132:133], v[156:157]
	v_pk_fma_f32 v[158:159], v[34:35], v[134:135], v[158:159]
	v_mul_f32_e32 v176, 0xbfb8aa3b, v152
	v_mul_f32_e32 v177, 0xbfb8aa3b, v153
	v_mul_f32_e32 v178, 0xbfb8aa3b, v154
	v_mul_f32_e32 v179, 0xbfb8aa3b, v155
	v_mul_f32_e32 v180, 0xbfb8aa3b, v156
	v_mul_f32_e32 v181, 0xbfb8aa3b, v157
	v_mul_f32_e32 v182, 0xbfb8aa3b, v158
	v_mul_f32_e32 v183, 0xbfb8aa3b, v159
	v_exp_f32_e32 v176, v176
	v_exp_f32_e32 v177, v177
	v_exp_f32_e32 v178, v178
	v_exp_f32_e32 v179, v179
	v_exp_f32_e32 v180, v180
	v_exp_f32_e32 v181, v181
	v_exp_f32_e32 v182, v182
	v_exp_f32_e32 v183, v183
	v_pk_add_f32 v[176:177], v[176:177], 1.0 op_sel_hi:[1,0]
	v_pk_add_f32 v[178:179], v[178:179], 1.0 op_sel_hi:[1,0]
	v_pk_add_f32 v[180:181], v[180:181], 1.0 op_sel_hi:[1,0]
	v_pk_add_f32 v[182:183], v[182:183], 1.0 op_sel_hi:[1,0]
	v_rcp_f32_e32 v176, v176
	v_rcp_f32_e32 v177, v177
	v_rcp_f32_e32 v178, v178
	v_rcp_f32_e32 v179, v179
	v_rcp_f32_e32 v180, v180
	v_rcp_f32_e32 v181, v181
	v_rcp_f32_e32 v182, v182
	v_rcp_f32_e32 v183, v183
	v_pk_mul_f32 v[152:153], v[152:153], v[176:177]
	v_pk_mul_f32 v[154:155], v[154:155], v[178:179]
	v_pk_mul_f32 v[156:157], v[156:157], v[180:181]
	v_pk_mul_f32 v[158:159], v[158:159], v[182:183]
	v_cvt_pk_bf16_f32 v176, v152, v153
	v_cvt_pk_bf16_f32 v177, v154, v155
	v_cvt_pk_bf16_f32 v178, v156, v157
	v_cvt_pk_bf16_f32 v179, v158, v159
	global_store_dwordx4 v2, v[176:179], s[48:49]
	s_add_u32 s48, s48, 0x4600
	s_addc_u32 s49, s49, 0
	s_waitcnt vmcnt(15)
	v_lshlrev_b32_e32 v136, 16, v68
	v_and_b32_e32 v137, 0xffff0000, v68
	v_lshlrev_b32_e32 v138, 16, v69
	v_and_b32_e32 v139, 0xffff0000, v69
	v_lshlrev_b32_e32 v140, 16, v70
	v_and_b32_e32 v141, 0xffff0000, v70
	v_lshlrev_b32_e32 v142, 16, v71
	v_and_b32_e32 v143, 0xffff0000, v71
	v_pk_fma_f32 v[152:153], v[4:5], v[144:145], v[36:37]
	v_pk_fma_f32 v[154:155], v[6:7], v[146:147], v[38:39]
	v_pk_fma_f32 v[156:157], v[8:9], v[148:149], v[40:41]
	v_pk_fma_f32 v[158:159], v[10:11], v[150:151], v[42:43]
	v_pk_fma_f32 v[152:153], v[12:13], v[120:121], v[152:153]
	v_pk_fma_f32 v[154:155], v[14:15], v[122:123], v[154:155]
	v_pk_fma_f32 v[156:157], v[16:17], v[124:125], v[156:157]
	v_pk_fma_f32 v[158:159], v[18:19], v[126:127], v[158:159]
	v_pk_fma_f32 v[152:153], v[20:21], v[128:129], v[152:153]
	v_pk_fma_f32 v[154:155], v[22:23], v[130:131], v[154:155]
	v_pk_fma_f32 v[156:157], v[24:25], v[132:133], v[156:157]
	v_pk_fma_f32 v[158:159], v[26:27], v[134:135], v[158:159]
	v_pk_fma_f32 v[152:153], v[28:29], v[136:137], v[152:153]
	v_pk_fma_f32 v[154:155], v[30:31], v[138:139], v[154:155]
	v_pk_fma_f32 v[156:157], v[32:33], v[140:141], v[156:157]
	v_pk_fma_f32 v[158:159], v[34:35], v[142:143], v[158:159]
	v_mul_f32_e32 v176, 0xbfb8aa3b, v152
	v_mul_f32_e32 v177, 0xbfb8aa3b, v153
	v_mul_f32_e32 v178, 0xbfb8aa3b, v154
	v_mul_f32_e32 v179, 0xbfb8aa3b, v155
	v_mul_f32_e32 v180, 0xbfb8aa3b, v156
	v_mul_f32_e32 v181, 0xbfb8aa3b, v157
	v_mul_f32_e32 v182, 0xbfb8aa3b, v158
	v_mul_f32_e32 v183, 0xbfb8aa3b, v159
	v_exp_f32_e32 v176, v176
	v_exp_f32_e32 v177, v177
	v_exp_f32_e32 v178, v178
	v_exp_f32_e32 v179, v179
	v_exp_f32_e32 v180, v180
	v_exp_f32_e32 v181, v181
	v_exp_f32_e32 v182, v182
	v_exp_f32_e32 v183, v183
	v_pk_add_f32 v[176:177], v[176:177], 1.0 op_sel_hi:[1,0]
	v_pk_add_f32 v[178:179], v[178:179], 1.0 op_sel_hi:[1,0]
	v_pk_add_f32 v[180:181], v[180:181], 1.0 op_sel_hi:[1,0]
	v_pk_add_f32 v[182:183], v[182:183], 1.0 op_sel_hi:[1,0]
	v_rcp_f32_e32 v176, v176
	v_rcp_f32_e32 v177, v177
	v_rcp_f32_e32 v178, v178
	v_rcp_f32_e32 v179, v179
	v_rcp_f32_e32 v180, v180
	v_rcp_f32_e32 v181, v181
	v_rcp_f32_e32 v182, v182
	v_rcp_f32_e32 v183, v183
	v_pk_mul_f32 v[152:153], v[152:153], v[176:177]
	v_pk_mul_f32 v[154:155], v[154:155], v[178:179]
	v_pk_mul_f32 v[156:157], v[156:157], v[180:181]
	v_pk_mul_f32 v[158:159], v[158:159], v[182:183]
	v_cvt_pk_bf16_f32 v176, v152, v153
	v_cvt_pk_bf16_f32 v177, v154, v155
	v_cvt_pk_bf16_f32 v178, v156, v157
	v_cvt_pk_bf16_f32 v179, v158, v159
	global_store_dwordx4 v2, v[176:179], s[48:49]
	s_add_u32 s48, s48, 0x4600
	s_addc_u32 s49, s49, 0
	s_waitcnt vmcnt(15)
; __device__ __forceinline__ unsigned pk2(float lo, float hi) { unsigned r; asm("v_cvt_pk_bf16_f32 %0, %1, %2" : "=v"(r) : "v"(lo), "v"(hi)); return r; }
; __device__ __forceinline__ float bflo(unsigned w) { return __uint_as_float(w << 16); }
; __device__ __forceinline__ float bfhi(unsigned w) { return __uint_as_float(w & 0xffff0000u); }
; __device__ __forceinline__ float siluf_(float x) { return x * __builtin_amdgcn_rcpf(1.f + __expf(-x)); }
; __device__ __forceinline__ void convbc_item(const Args& a, int layer, bool is_sample, int b, int cg32, int seq_row0, bf16_t* proj, const int tid) {
;     ...
;                 for (int i = 0; i < 8; ++i) o[i] = cb[i];
; #pragma unroll
;                 for (int k = 0; k < 4; ++k) { const u32x4 w = rw[t + k];
;                     o[0] += cw[k][0] * bflo(w.x); o[1] += cw[k][1] * bfhi(w.x); o[2] += cw[k][2] * bflo(w.y); o[3] += cw[k][3] * bfhi(w.y);
;                     o[4] += cw[k][4] * bflo(w.z); o[5] += cw[k][5] * bfhi(w.z); o[6] += cw[k][6] * bflo(w.w); o[7] += cw[k][7] * bfhi(w.w); }
;                 u32x4 w; w.x = pk2(siluf_(o[0]), siluf_(o[1])); w.y = pk2(siluf_(o[2]), siluf_(o[3])); w.z = pk2(siluf_(o[4]), siluf_(o[5])); w.w = pk2(siluf_(o[6]), siluf_(o[7]));
;                 *(u32x4*)(proj + (size_t)(seq_row0 + t0 + t) * PN + C_XBC + ch) = w;
	v_lshlrev_b32_e32 v144, 16, v72
	v_and_b32_e32 v145, 0xffff0000, v72
	v_lshlrev_b32_e32 v146, 16, v73
	v_and_b32_e32 v147, 0xffff0000, v73
	v_lshlrev_b32_e32 v148, 16, v74
	v_and_b32_e32 v149, 0xffff0000, v74
	v_lshlrev_b32_e32 v150, 16, v75
	v_and_b32_e32 v151, 0xffff0000, v75
	v_pk_fma_f32 v[152:153], v[4:5], v[120:121], v[36:37]
	v_pk_fma_f32 v[154:155], v[6:7], v[122:123], v[38:39]
	v_pk_fma_f32 v[156:157], v[8:9], v[124:125], v[40:41]
	v_pk_fma_f32 v[158:159], v[10:11], v[126:127], v[42:43]
	v_pk_fma_f32 v[152:153], v[12:13], v[128:129], v[152:153]
	v_pk_fma_f32 v[154:155], v[14:15], v[130:131], v[154:155]
	v_pk_fma_f32 v[156:157], v[16:17], v[132:133], v[156:157]
	v_pk_fma_f32 v[158:159], v[18:19], v[134:135], v[158:159]
	v_pk_fma_f32 v[152:153], v[20:21], v[136:137], v[152:153]
	v_pk_fma_f32 v[154:155], v[22:23], v[138:139], v[154:155]
	v_pk_fma_f32 v[156:157], v[24:25], v[140:141], v[156:157]
	v_pk_fma_f32 v[158:159], v[26:27], v[142:143], v[158:159]
	v_pk_fma_f32 v[152:153], v[28:29], v[144:145], v[152:153]
	v_pk_fma_f32 v[154:155], v[30:31], v[146:147], v[154:155]
	v_pk_fma_f32 v[156:157], v[32:33], v[148:149], v[156:157]
	v_pk_fma_f32 v[158:159], v[34:35], v[150:151], v[158:159]
	v_mul_f32_e32 v176, 0xbfb8aa3b, v152
	v_mul_f32_e32 v177, 0xbfb8aa3b, v153
	v_mul_f32_e32 v178, 0xbfb8aa3b, v154
	v_mul_f32_e32 v179, 0xbfb8aa3b, v155
	v_mul_f32_e32 v180, 0xbfb8aa3b, v156
	v_mul_f32_e32 v181, 0xbfb8aa3b, v157
	v_mul_f32_e32 v182, 0xbfb8aa3b, v158
	v_mul_f32_e32 v183, 0xbfb8aa3b, v159
	v_exp_f32_e32 v176, v176
	v_exp_f32_e32 v177, v177
	v_exp_f32_e32 v178, v178
	v_exp_f32_e32 v179, v179
	v_exp_f32_e32 v180, v180
	v_exp_f32_e32 v181, v181
	v_exp_f32_e32 v182, v182
	v_exp_f32_e32 v183, v183
	v_pk_add_f32 v[176:177], v[176:177], 1.0 op_sel_hi:[1,0]
	v_pk_add_f32 v[178:179], v[178:179], 1.0 op_sel_hi:[1,0]
	v_pk_add_f32 v[180:181], v[180:181], 1.0 op_sel_hi:[1,0]
	v_pk_add_f32 v[182:183], v[182:183], 1.0 op_sel_hi:[1,0]
	v_rcp_f32_e32 v176, v176
	v_rcp_f32_e32 v177, v177
	v_rcp_f32_e32 v178, v178
	v_rcp_f32_e32 v179, v179
	v_rcp_f32_e32 v180, v180
	v_rcp_f32_e32 v181, v181
	v_rcp_f32_e32 v182, v182
	v_rcp_f32_e32 v183, v183
	v_pk_mul_f32 v[152:153], v[152:153], v[176:177]
	v_pk_mul_f32 v[154:155], v[154:155], v[178:179]
	v_pk_mul_f32 v[156:157], v[156:157], v[180:181]
	v_pk_mul_f32 v[158:159], v[158:159], v[182:183]
	v_cvt_pk_bf16_f32 v176, v152, v153
	v_cvt_pk_bf16_f32 v177, v154, v155
	v_cvt_pk_bf16_f32 v178, v156, v157
	v_cvt_pk_bf16_f32 v179, v158, v159
	global_store_dwordx4 v2, v[176:179], s[48:49]
	s_add_u32 s48, s48, 0x4600
	s_addc_u32 s49, s49, 0
	s_waitcnt vmcnt(15)
	v_lshlrev_b32_e32 v120, 16, v76
	v_and_b32_e32 v121, 0xffff0000, v76
	v_lshlrev_b32_e32 v122, 16, v77
	v_and_b32_e32 v123, 0xffff0000, v77
	v_lshlrev_b32_e32 v124, 16, v78
	v_and_b32_e32 v125, 0xffff0000, v78
	v_lshlrev_b32_e32 v126, 16, v79
	v_and_b32_e32 v127, 0xffff0000, v79
	v_pk_fma_f32 v[152:153], v[4:5], v[128:129], v[36:37]
	v_pk_fma_f32 v[154:155], v[6:7], v[130:131], v[38:39]
	v_pk_fma_f32 v[156:157], v[8:9], v[132:133], v[40:41]
	v_pk_fma_f32 v[158:159], v[10:11], v[134:135], v[42:43]
	v_pk_fma_f32 v[152:153], v[12:13], v[136:137], v[152:153]
	v_pk_fma_f32 v[154:155], v[14:15], v[138:139], v[154:155]
	v_pk_fma_f32 v[156:157], v[16:17], v[140:141], v[156:157]
	v_pk_fma_f32 v[158:159], v[18:19], v[142:143], v[158:159]
	v_pk_fma_f32 v[152:153], v[20:21], v[144:145], v[152:153]
	v_pk_fma_f32 v[154:155], v[22:23], v[146:147], v[154:155]
	v_pk_fma_f32 v[156:157], v[24:25], v[148:149], v[156:157]
	v_pk_fma_f32 v[158:159], v[26:27], v[150:151], v[158:159]
	v_pk_fma_f32 v[152:153], v[28:29], v[120:121], v[152:153]
	v_pk_fma_f32 v[154:155], v[30:31], v[122:123], v[154:155]
	v_pk_fma_f32 v[156:157], v[32:33], v[124:125], v[156:157]
	v_pk_fma_f32 v[158:159], v[34:35], v[126:127], v[158:159]
	v_mul_f32_e32 v176, 0xbfb8aa3b, v152
	v_mul_f32_e32 v177, 0xbfb8aa3b, v153
	v_mul_f32_e32 v178, 0xbfb8aa3b, v154
	v_mul_f32_e32 v179, 0xbfb8aa3b, v155
	v_mul_f32_e32 v180, 0xbfb8aa3b, v156
	v_mul_f32_e32 v181, 0xbfb8aa3b, v157
	v_mul_f32_e32 v182, 0xbfb8aa3b, v158
	v_mul_f32_e32 v183, 0xbfb8aa3b, v159
	v_exp_f32_e32 v176, v176
	v_exp_f32_e32 v177, v177
	v_exp_f32_e32 v178, v178
	v_exp_f32_e32 v179, v179
	v_exp_f32_e32 v180, v180
	v_exp_f32_e32 v181, v181
	v_exp_f32_e32 v182, v182
	v_exp_f32_e32 v183, v183
	v_pk_add_f32 v[176:177], v[176:177], 1.0 op_sel_hi:[1,0]
	v_pk_add_f32 v[178:179], v[178:179], 1.0 op_sel_hi:[1,0]
	v_pk_add_f32 v[180:181], v[180:181], 1.0 op_sel_hi:[1,0]
	v_pk_add_f32 v[182:183], v[182:183], 1.0 op_sel_hi:[1,0]
	v_rcp_f32_e32 v176, v176
	v_rcp_f32_e32 v177, v177
	v_rcp_f32_e32 v178, v178
	v_rcp_f32_e32 v179, v179
	v_rcp_f32_e32 v180, v180
	v_rcp_f32_e32 v181, v181
	v_rcp_f32_e32 v182, v182
	v_rcp_f32_e32 v183, v183
	v_pk_mul_f32 v[152:153], v[152:153], v[176:177]
	v_pk_mul_f32 v[154:155], v[154:155], v[178:179]
	v_pk_mul_f32 v[156:157], v[156:157], v[180:181]
	v_pk_mul_f32 v[158:159], v[158:159], v[182:183]
	v_cvt_pk_bf16_f32 v176, v152, v153
	v_cvt_pk_bf16_f32 v177, v154, v155
	v_cvt_pk_bf16_f32 v178, v156, v157
	v_cvt_pk_bf16_f32 v179, v158, v159
	global_store_dwordx4 v2, v[176:179], s[48:49]
	s_add_u32 s48, s48, 0x4600
	s_addc_u32 s49, s49, 0
	s_waitcnt vmcnt(15)
; __device__ __forceinline__ unsigned pk2(float lo, float hi) { unsigned r; asm("v_cvt_pk_bf16_f32 %0, %1, %2" : "=v"(r) : "v"(lo), "v"(hi)); return r; }
; __device__ __forceinline__ float bflo(unsigned w) { return __uint_as_float(w << 16); }
; __device__ __forceinline__ float bfhi(unsigned w) { return __uint_as_float(w & 0xffff0000u); }
; __device__ __forceinline__ float siluf_(float x) { return x * __builtin_amdgcn_rcpf(1.f + __expf(-x)); }
; __device__ __forceinline__ void convbc_item(const Args& a, int layer, bool is_sample, int b, int cg32, int seq_row0, bf16_t* proj, const int tid) {
;     ...
;                 for (int i = 0; i < 8; ++i) o[i] = cb[i];
; #pragma unroll
;                 for (int k = 0; k < 4; ++k) { const u32x4 w = rw[t + k];
;                     o[0] += cw[k][0] * bflo(w.x); o[1] += cw[k][1] * bfhi(w.x); o[2] += cw[k][2] * bflo(w.y); o[3] += cw[k][3] * bfhi(w.y);
;                     o[4] += cw[k][4] * bflo(w.z); o[5] += cw[k][5] * bfhi(w.z); o[6] += cw[k][6] * bflo(w.w); o[7] += cw[k][7] * bfhi(w.w); }
;                 u32x4 w; w.x = pk2(siluf_(o[0]), siluf_(o[1])); w.y = pk2(siluf_(o[2]), siluf_(o[3])); w.z = pk2(siluf_(o[4]), siluf_(o[5])); w.w = pk2(siluf_(o[6]), siluf_(o[7]));
;                 *(u32x4*)(proj + (size_t)(seq_row0 + t0 + t) * PN + C_XBC + ch) = w;
	v_lshlrev_b32_e32 v128, 16, v80
	v_and_b32_e32 v129, 0xffff0000, v80
	v_lshlrev_b32_e32 v130, 16, v81
	v_and_b32_e32 v131, 0xffff0000, v81
	v_lshlrev_b32_e32 v132, 16, v82
	v_and_b32_e32 v133, 0xffff0000, v82
	v_lshlrev_b32_e32 v134, 16, v83
	v_and_b32_e32 v135, 0xffff0000, v83
	v_pk_fma_f32 v[152:153], v[4:5], v[136:137], v[36:37]
	v_pk_fma_f32 v[154:155], v[6:7], v[138:139], v[38:39]
	v_pk_fma_f32 v[156:157], v[8:9], v[140:141], v[40:41]
	v_pk_fma_f32 v[158:159], v[10:11], v[142:143], v[42:43]
	v_pk_fma_f32 v[152:153], v[12:13], v[144:145], v[152:153]
	v_pk_fma_f32 v[154:155], v[14:15], v[146:147], v[154:155]
	v_pk_fma_f32 v[156:157], v[16:17], v[148:149], v[156:157]
	v_pk_fma_f32 v[158:159], v[18:19], v[150:151], v[158:159]
	v_pk_fma_f32 v[152:153], v[20:21], v[120:121], v[152:153]
	v_pk_fma_f32 v[154:155], v[22:23], v[122:123], v[154:155]
	v_pk_fma_f32 v[156:157], v[24:25], v[124:125], v[156:157]
	v_pk_fma_f32 v[158:159], v[26:27], v[126:127], v[158:159]
	v_pk_fma_f32 v[152:153], v[28:29], v[128:129], v[152:153]
	v_pk_fma_f32 v[154:155], v[30:31], v[130:131], v[154:155]
	v_pk_fma_f32 v[156:157], v[32:33], v[132:133], v[156:157]
	v_pk_fma_f32 v[158:159], v[34:35], v[134:135], v[158:159]
	v_mul_f32_e32 v176, 0xbfb8aa3b, v152
	v_mul_f32_e32 v177, 0xbfb8aa3b, v153
	v_mul_f32_e32 v178, 0xbfb8aa3b, v154
	v_mul_f32_e32 v179, 0xbfb8aa3b, v155
	v_mul_f32_e32 v180, 0xbfb8aa3b, v156
	v_mul_f32_e32 v181, 0xbfb8aa3b, v157
	v_mul_f32_e32 v182, 0xbfb8aa3b, v158
	v_mul_f32_e32 v183, 0xbfb8aa3b, v159
	v_exp_f32_e32 v176, v176
	v_exp_f32_e32 v177, v177
	v_exp_f32_e32 v178, v178
	v_exp_f32_e32 v179, v179
	v_exp_f32_e32 v180, v180
	v_exp_f32_e32 v181, v181
	v_exp_f32_e32 v182, v182
	v_exp_f32_e32 v183, v183
	v_pk_add_f32 v[176:177], v[176:177], 1.0 op_sel_hi:[1,0]
	v_pk_add_f32 v[178:179], v[178:179], 1.0 op_sel_hi:[1,0]
	v_pk_add_f32 v[180:181], v[180:181], 1.0 op_sel_hi:[1,0]
	v_pk_add_f32 v[182:183], v[182:183], 1.0 op_sel_hi:[1,0]
	v_rcp_f32_e32 v176, v176
	v_rcp_f32_e32 v177, v177
	v_rcp_f32_e32 v178, v178
	v_rcp_f32_e32 v179, v179
	v_rcp_f32_e32 v180, v180
	v_rcp_f32_e32 v181, v181
	v_rcp_f32_e32 v182, v182
	v_rcp_f32_e32 v183, v183
	v_pk_mul_f32 v[152:153], v[152:153], v[176:177]
	v_pk_mul_f32 v[154:155], v[154:155], v[178:179]
	v_pk_mul_f32 v[156:157], v[156:157], v[180:181]
	v_pk_mul_f32 v[158:159], v[158:159], v[182:183]
	v_cvt_pk_bf16_f32 v176, v152, v153
	v_cvt_pk_bf16_f32 v177, v154, v155
	v_cvt_pk_bf16_f32 v178, v156, v157
	v_cvt_pk_bf16_f32 v179, v158, v159
	global_store_dwordx4 v2, v[176:179], s[48:49]
	s_add_u32 s48, s48, 0x4600
	s_addc_u32 s49, s49, 0
	s_waitcnt vmcnt(15)
	v_lshlrev_b32_e32 v136, 16, v88
	v_and_b32_e32 v137, 0xffff0000, v88
	v_lshlrev_b32_e32 v138, 16, v89
	v_and_b32_e32 v139, 0xffff0000, v89
	v_lshlrev_b32_e32 v140, 16, v90
	v_and_b32_e32 v141, 0xffff0000, v90
	v_lshlrev_b32_e32 v142, 16, v91
	v_and_b32_e32 v143, 0xffff0000, v91
	v_pk_fma_f32 v[152:153], v[4:5], v[144:145], v[36:37]
	v_pk_fma_f32 v[154:155], v[6:7], v[146:147], v[38:39]
	v_pk_fma_f32 v[156:157], v[8:9], v[148:149], v[40:41]
	v_pk_fma_f32 v[158:159], v[10:11], v[150:151], v[42:43]
	v_pk_fma_f32 v[152:153], v[12:13], v[120:121], v[152:153]
	v_pk_fma_f32 v[154:155], v[14:15], v[122:123], v[154:155]
	v_pk_fma_f32 v[156:157], v[16:17], v[124:125], v[156:157]
	v_pk_fma_f32 v[158:159], v[18:19], v[126:127], v[158:159]
	v_pk_fma_f32 v[152:153], v[20:21], v[128:129], v[152:153]
	v_pk_fma_f32 v[154:155], v[22:23], v[130:131], v[154:155]
	v_pk_fma_f32 v[156:157], v[24:25], v[132:133], v[156:157]
	v_pk_fma_f32 v[158:159], v[26:27], v[134:135], v[158:159]
	v_pk_fma_f32 v[152:153], v[28:29], v[136:137], v[152:153]
	v_pk_fma_f32 v[154:155], v[30:31], v[138:139], v[154:155]
	v_pk_fma_f32 v[156:157], v[32:33], v[140:141], v[156:157]
	v_pk_fma_f32 v[158:159], v[34:35], v[142:143], v[158:159]
	v_mul_f32_e32 v176, 0xbfb8aa3b, v152
	v_mul_f32_e32 v177, 0xbfb8aa3b, v153
	v_mul_f32_e32 v178, 0xbfb8aa3b, v154
	v_mul_f32_e32 v179, 0xbfb8aa3b, v155
	v_mul_f32_e32 v180, 0xbfb8aa3b, v156
	v_mul_f32_e32 v181, 0xbfb8aa3b, v157
	v_mul_f32_e32 v182, 0xbfb8aa3b, v158
	v_mul_f32_e32 v183, 0xbfb8aa3b, v159
	v_exp_f32_e32 v176, v176
	v_exp_f32_e32 v177, v177
	v_exp_f32_e32 v178, v178
	v_exp_f32_e32 v179, v179
	v_exp_f32_e32 v180, v180
	v_exp_f32_e32 v181, v181
	v_exp_f32_e32 v182, v182
	v_exp_f32_e32 v183, v183
	v_pk_add_f32 v[176:177], v[176:177], 1.0 op_sel_hi:[1,0]
	v_pk_add_f32 v[178:179], v[178:179], 1.0 op_sel_hi:[1,0]
	v_pk_add_f32 v[180:181], v[180:181], 1.0 op_sel_hi:[1,0]
	v_pk_add_f32 v[182:183], v[182:183], 1.0 op_sel_hi:[1,0]
	v_rcp_f32_e32 v176, v176
	v_rcp_f32_e32 v177, v177
	v_rcp_f32_e32 v178, v178
	v_rcp_f32_e32 v179, v179
	v_rcp_f32_e32 v180, v180
	v_rcp_f32_e32 v181, v181
	v_rcp_f32_e32 v182, v182
	v_rcp_f32_e32 v183, v183
	v_pk_mul_f32 v[152:153], v[152:153], v[176:177]
	v_pk_mul_f32 v[154:155], v[154:155], v[178:179]
	v_pk_mul_f32 v[156:157], v[156:157], v[180:181]
	v_pk_mul_f32 v[158:159], v[158:159], v[182:183]
	v_cvt_pk_bf16_f32 v176, v152, v153
	v_cvt_pk_bf16_f32 v177, v154, v155
	v_cvt_pk_bf16_f32 v178, v156, v157
	v_cvt_pk_bf16_f32 v179, v158, v159
	global_store_dwordx4 v2, v[176:179], s[48:49]
	s_add_u32 s48, s48, 0x4600
	s_addc_u32 s49, s49, 0
	s_waitcnt vmcnt(15)
; __device__ __forceinline__ unsigned pk2(float lo, float hi) { unsigned r; asm("v_cvt_pk_bf16_f32 %0, %1, %2" : "=v"(r) : "v"(lo), "v"(hi)); return r; }
; __device__ __forceinline__ float bflo(unsigned w) { return __uint_as_float(w << 16); }
; __device__ __forceinline__ float bfhi(unsigned w) { return __uint_as_float(w & 0xffff0000u); }
; __device__ __forceinline__ float siluf_(float x) { return x * __builtin_amdgcn_rcpf(1.f + __expf(-x)); }
; __device__ __forceinline__ void convbc_item(const Args& a, int layer, bool is_sample, int b, int cg32, int seq_row0, bf16_t* proj, const int tid) {
;     ...
;                 for (int i = 0; i < 8; ++i) o[i] = cb[i];
; #pragma unroll
;                 for (int k = 0; k < 4; ++k) { const u32x4 w = rw[t + k];
;                     o[0] += cw[k][0] * bflo(w.x); o[1] += cw[k][1] * bfhi(w.x); o[2] += cw[k][2] * bflo(w.y); o[3] += cw[k][3] * bfhi(w.y);
;                     o[4] += cw[k][4] * bflo(w.z); o[5] += cw[k][5] * bfhi(w.z); o[6] += cw[k][6] * bflo(w.w); o[7] += cw[k][7] * bfhi(w.w); }
;                 u32x4 w; w.x = pk2(siluf_(o[0]), siluf_(o[1])); w.y = pk2(siluf_(o[2]), siluf_(o[3])); w.z = pk2(siluf_(o[4]), siluf_(o[5])); w.w = pk2(siluf_(o[6]), siluf_(o[7]));
;                 *(u32x4*)(proj + (size_t)(seq_row0 + t0 + t) * PN + C_XBC + ch) = w;
	v_lshlrev_b32_e32 v144, 16, v92
	v_and_b32_e32 v145, 0xffff0000, v92
	v_lshlrev_b32_e32 v146, 16, v93
	v_and_b32_e32 v147, 0xffff0000, v93
	v_lshlrev_b32_e32 v148, 16, v94
	v_and_b32_e32 v149, 0xffff0000, v94
	v_lshlrev_b32_e32 v150, 16, v95
	v_and_b32_e32 v151, 0xffff0000, v95
	v_pk_fma_f32 v[152:153], v[4:5], v[120:121], v[36:37]
	v_pk_fma_f32 v[154:155], v[6:7], v[122:123], v[38:39]
	v_pk_fma_f32 v[156:157], v[8:9], v[124:125], v[40:41]
	v_pk_fma_f32 v[158:159], v[10:11], v[126:127], v[42:43]
	v_pk_fma_f32 v[152:153], v[12:13], v[128:129], v[152:153]
	v_pk_fma_f32 v[154:155], v[14:15], v[130:131], v[154:155]
	v_pk_fma_f32 v[156:157], v[16:17], v[132:133], v[156:157]
	v_pk_fma_f32 v[158:159], v[18:19], v[134:135], v[158:159]
	v_pk_fma_f32 v[152:153], v[20:21], v[136:137], v[152:153]
	v_pk_fma_f32 v[154:155], v[22:23], v[138:139], v[154:155]
	v_pk_fma_f32 v[156:157], v[24:25], v[140:141], v[156:157]
	v_pk_fma_f32 v[158:159], v[26:27], v[142:143], v[158:159]
	v_pk_fma_f32 v[152:153], v[28:29], v[144:145], v[152:153]
	v_pk_fma_f32 v[154:155], v[30:31], v[146:147], v[154:155]
	v_pk_fma_f32 v[156:157], v[32:33], v[148:149], v[156:157]
	v_pk_fma_f32 v[158:159], v[34:35], v[150:151], v[158:159]
	v_mul_f32_e32 v176, 0xbfb8aa3b, v152
	v_mul_f32_e32 v177, 0xbfb8aa3b, v153
	v_mul_f32_e32 v178, 0xbfb8aa3b, v154
	v_mul_f32_e32 v179, 0xbfb8aa3b, v155
	v_mul_f32_e32 v180, 0xbfb8aa3b, v156
	v_mul_f32_e32 v181, 0xbfb8aa3b, v157
	v_mul_f32_e32 v182, 0xbfb8aa3b, v158
	v_mul_f32_e32 v183, 0xbfb8aa3b, v159
	v_exp_f32_e32 v176, v176
	v_exp_f32_e32 v177, v177
	v_exp_f32_e32 v178, v178
	v_exp_f32_e32 v179, v179
	v_exp_f32_e32 v180, v180
	v_exp_f32_e32 v181, v181
	v_exp_f32_e32 v182, v182
	v_exp_f32_e32 v183, v183
	v_pk_add_f32 v[176:177], v[176:177], 1.0 op_sel_hi:[1,0]
	v_pk_add_f32 v[178:179], v[178:179], 1.0 op_sel_hi:[1,0]
	v_pk_add_f32 v[180:181], v[180:181], 1.0 op_sel_hi:[1,0]
	v_pk_add_f32 v[182:183], v[182:183], 1.0 op_sel_hi:[1,0]
	v_rcp_f32_e32 v176, v176
	v_rcp_f32_e32 v177, v177
	v_rcp_f32_e32 v178, v178
	v_rcp_f32_e32 v179, v179
	v_rcp_f32_e32 v180, v180
	v_rcp_f32_e32 v181, v181
	v_rcp_f32_e32 v182, v182
	v_rcp_f32_e32 v183, v183
	v_pk_mul_f32 v[152:153], v[152:153], v[176:177]
	v_pk_mul_f32 v[154:155], v[154:155], v[178:179]
	v_pk_mul_f32 v[156:157], v[156:157], v[180:181]
	v_pk_mul_f32 v[158:159], v[158:159], v[182:183]
	v_cvt_pk_bf16_f32 v176, v152, v153
	v_cvt_pk_bf16_f32 v177, v154, v155
	v_cvt_pk_bf16_f32 v178, v156, v157
	v_cvt_pk_bf16_f32 v179, v158, v159
	global_store_dwordx4 v2, v[176:179], s[48:49]
	s_add_u32 s48, s48, 0x4600
	s_addc_u32 s49, s49, 0
	s_waitcnt vmcnt(15)
	v_lshlrev_b32_e32 v120, 16, v96
	v_and_b32_e32 v121, 0xffff0000, v96
	v_lshlrev_b32_e32 v122, 16, v97
	v_and_b32_e32 v123, 0xffff0000, v97
	v_lshlrev_b32_e32 v124, 16, v98
	v_and_b32_e32 v125, 0xffff0000, v98
	v_lshlrev_b32_e32 v126, 16, v99
	v_and_b32_e32 v127, 0xffff0000, v99
	v_pk_fma_f32 v[152:153], v[4:5], v[128:129], v[36:37]
	v_pk_fma_f32 v[154:155], v[6:7], v[130:131], v[38:39]
	v_pk_fma_f32 v[156:157], v[8:9], v[132:133], v[40:41]
	v_pk_fma_f32 v[158:159], v[10:11], v[134:135], v[42:43]
	v_pk_fma_f32 v[152:153], v[12:13], v[136:137], v[152:153]
	v_pk_fma_f32 v[154:155], v[14:15], v[138:139], v[154:155]
	v_pk_fma_f32 v[156:157], v[16:17], v[140:141], v[156:157]
	v_pk_fma_f32 v[158:159], v[18:19], v[142:143], v[158:159]
	v_pk_fma_f32 v[152:153], v[20:21], v[144:145], v[152:153]
	v_pk_fma_f32 v[154:155], v[22:23], v[146:147], v[154:155]
	v_pk_fma_f32 v[156:157], v[24:25], v[148:149], v[156:157]
	v_pk_fma_f32 v[158:159], v[26:27], v[150:151], v[158:159]
	v_pk_fma_f32 v[152:153], v[28:29], v[120:121], v[152:153]
	v_pk_fma_f32 v[154:155], v[30:31], v[122:123], v[154:155]
	v_pk_fma_f32 v[156:157], v[32:33], v[124:125], v[156:157]
	v_pk_fma_f32 v[158:159], v[34:35], v[126:127], v[158:159]
	v_mul_f32_e32 v176, 0xbfb8aa3b, v152
	v_mul_f32_e32 v177, 0xbfb8aa3b, v153
	v_mul_f32_e32 v178, 0xbfb8aa3b, v154
	v_mul_f32_e32 v179, 0xbfb8aa3b, v155
	v_mul_f32_e32 v180, 0xbfb8aa3b, v156
	v_mul_f32_e32 v181, 0xbfb8aa3b, v157
	v_mul_f32_e32 v182, 0xbfb8aa3b, v158
	v_mul_f32_e32 v183, 0xbfb8aa3b, v159
	v_exp_f32_e32 v176, v176
	v_exp_f32_e32 v177, v177
	v_exp_f32_e32 v178, v178
	v_exp_f32_e32 v179, v179
	v_exp_f32_e32 v180, v180
	v_exp_f32_e32 v181, v181
	v_exp_f32_e32 v182, v182
	v_exp_f32_e32 v183, v183
	v_pk_add_f32 v[176:177], v[176:177], 1.0 op_sel_hi:[1,0]
	v_pk_add_f32 v[178:179], v[178:179], 1.0 op_sel_hi:[1,0]
	v_pk_add_f32 v[180:181], v[180:181], 1.0 op_sel_hi:[1,0]
	v_pk_add_f32 v[182:183], v[182:183], 1.0 op_sel_hi:[1,0]
	v_rcp_f32_e32 v176, v176
	v_rcp_f32_e32 v177, v177
	v_rcp_f32_e32 v178, v178
	v_rcp_f32_e32 v179, v179
	v_rcp_f32_e32 v180, v180
	v_rcp_f32_e32 v181, v181
	v_rcp_f32_e32 v182, v182
	v_rcp_f32_e32 v183, v183
	v_pk_mul_f32 v[152:153], v[152:153], v[176:177]
	v_pk_mul_f32 v[154:155], v[154:155], v[178:179]
	v_pk_mul_f32 v[156:157], v[156:157], v[180:181]
	v_pk_mul_f32 v[158:159], v[158:159], v[182:183]
	v_cvt_pk_bf16_f32 v176, v152, v153
	v_cvt_pk_bf16_f32 v177, v154, v155
	v_cvt_pk_bf16_f32 v178, v156, v157
	v_cvt_pk_bf16_f32 v179, v158, v159
	global_store_dwordx4 v2, v[176:179], s[48:49]
	s_add_u32 s48, s48, 0x4600
	s_addc_u32 s49, s49, 0
	s_waitcnt vmcnt(15)
; __device__ __forceinline__ unsigned pk2(float lo, float hi) { unsigned r; asm("v_cvt_pk_bf16_f32 %0, %1, %2" : "=v"(r) : "v"(lo), "v"(hi)); return r; }
; __device__ __forceinline__ float bflo(unsigned w) { return __uint_as_float(w << 16); }
; __device__ __forceinline__ float bfhi(unsigned w) { return __uint_as_float(w & 0xffff0000u); }
; __device__ __forceinline__ float siluf_(float x) { return x * __builtin_amdgcn_rcpf(1.f + __expf(-x)); }
; __device__ __forceinline__ void convbc_item(const Args& a, int layer, bool is_sample, int b, int cg32, int seq_row0, bf16_t* proj, const int tid) {
;     ...
;                 for (int i = 0; i < 8; ++i) o[i] = cb[i];
; #pragma unroll
;                 for (int k = 0; k < 4; ++k) { const u32x4 w = rw[t + k];
;                     o[0] += cw[k][0] * bflo(w.x); o[1] += cw[k][1] * bfhi(w.x); o[2] += cw[k][2] * bflo(w.y); o[3] += cw[k][3] * bfhi(w.y);
;                     o[4] += cw[k][4] * bflo(w.z); o[5] += cw[k][5] * bfhi(w.z); o[6] += cw[k][6] * bflo(w.w); o[7] += cw[k][7] * bfhi(w.w); }
;                 u32x4 w; w.x = pk2(siluf_(o[0]), siluf_(o[1])); w.y = pk2(siluf_(o[2]), siluf_(o[3])); w.z = pk2(siluf_(o[4]), siluf_(o[5])); w.w = pk2(siluf_(o[6]), siluf_(o[7]));
;                 *(u32x4*)(proj + (size_t)(seq_row0 + t0 + t) * PN + C_XBC + ch) = w;
	v_lshlrev_b32_e32 v128, 16, v104
	v_and_b32_e32 v129, 0xffff0000, v104
	v_lshlrev_b32_e32 v130, 16, v105
	v_and_b32_e32 v131, 0xffff0000, v105
	v_lshlrev_b32_e32 v132, 16, v106
	v_and_b32_e32 v133, 0xffff0000, v106
	v_lshlrev_b32_e32 v134, 16, v107
	v_and_b32_e32 v135, 0xffff0000, v107
	v_pk_fma_f32 v[152:153], v[4:5], v[136:137], v[36:37]
	v_pk_fma_f32 v[154:155], v[6:7], v[138:139], v[38:39]
	v_pk_fma_f32 v[156:157], v[8:9], v[140:141], v[40:41]
	v_pk_fma_f32 v[158:159], v[10:11], v[142:143], v[42:43]
	v_pk_fma_f32 v[152:153], v[12:13], v[144:145], v[152:153]
	v_pk_fma_f32 v[154:155], v[14:15], v[146:147], v[154:155]
	v_pk_fma_f32 v[156:157], v[16:17], v[148:149], v[156:157]
	v_pk_fma_f32 v[158:159], v[18:19], v[150:151], v[158:159]
	v_pk_fma_f32 v[152:153], v[20:21], v[120:121], v[152:153]
	v_pk_fma_f32 v[154:155], v[22:23], v[122:123], v[154:155]
	v_pk_fma_f32 v[156:157], v[24:25], v[124:125], v[156:157]
	v_pk_fma_f32 v[158:159], v[26:27], v[126:127], v[158:159]
	v_pk_fma_f32 v[152:153], v[28:29], v[128:129], v[152:153]
	v_pk_fma_f32 v[154:155], v[30:31], v[130:131], v[154:155]
	v_pk_fma_f32 v[156:157], v[32:33], v[132:133], v[156:157]
	v_pk_fma_f32 v[158:159], v[34:35], v[134:135], v[158:159]
	v_mul_f32_e32 v176, 0xbfb8aa3b, v152
	v_mul_f32_e32 v177, 0xbfb8aa3b, v153
	v_mul_f32_e32 v178, 0xbfb8aa3b, v154
	v_mul_f32_e32 v179, 0xbfb8aa3b, v155
	v_mul_f32_e32 v180, 0xbfb8aa3b, v156
	v_mul_f32_e32 v181, 0xbfb8aa3b, v157
	v_mul_f32_e32 v182, 0xbfb8aa3b, v158
	v_mul_f32_e32 v183, 0xbfb8aa3b, v159
	v_exp_f32_e32 v176, v176
	v_exp_f32_e32 v177, v177
	v_exp_f32_e32 v178, v178
	v_exp_f32_e32 v179, v179
	v_exp_f32_e32 v180, v180
	v_exp_f32_e32 v181, v181
	v_exp_f32_e32 v182, v182
	v_exp_f32_e32 v183, v183
	v_pk_add_f32 v[176:177], v[176:177], 1.0 op_sel_hi:[1,0]
	v_pk_add_f32 v[178:179], v[178:179], 1.0 op_sel_hi:[1,0]
	v_pk_add_f32 v[180:181], v[180:181], 1.0 op_sel_hi:[1,0]
	v_pk_add_f32 v[182:183], v[182:183], 1.0 op_sel_hi:[1,0]
	v_rcp_f32_e32 v176, v176
	v_rcp_f32_e32 v177, v177
	v_rcp_f32_e32 v178, v178
	v_rcp_f32_e32 v179, v179
	v_rcp_f32_e32 v180, v180
	v_rcp_f32_e32 v181, v181
	v_rcp_f32_e32 v182, v182
	v_rcp_f32_e32 v183, v183
	v_pk_mul_f32 v[152:153], v[152:153], v[176:177]
	v_pk_mul_f32 v[154:155], v[154:155], v[178:179]
	v_pk_mul_f32 v[156:157], v[156:157], v[180:181]
	v_pk_mul_f32 v[158:159], v[158:159], v[182:183]
	v_cvt_pk_bf16_f32 v176, v152, v153
	v_cvt_pk_bf16_f32 v177, v154, v155
	v_cvt_pk_bf16_f32 v178, v156, v157
	v_cvt_pk_bf16_f32 v179, v158, v159
	global_store_dwordx4 v2, v[176:179], s[48:49]
	s_add_u32 s48, s48, 0x4600
	s_addc_u32 s49, s49, 0
	s_waitcnt vmcnt(15)
	v_lshlrev_b32_e32 v136, 16, v108
	v_and_b32_e32 v137, 0xffff0000, v108
	v_lshlrev_b32_e32 v138, 16, v109
	v_and_b32_e32 v139, 0xffff0000, v109
	v_lshlrev_b32_e32 v140, 16, v110
	v_and_b32_e32 v141, 0xffff0000, v110
	v_lshlrev_b32_e32 v142, 16, v111
	v_and_b32_e32 v143, 0xffff0000, v111
	v_pk_fma_f32 v[152:153], v[4:5], v[144:145], v[36:37]
	v_pk_fma_f32 v[154:155], v[6:7], v[146:147], v[38:39]
	v_pk_fma_f32 v[156:157], v[8:9], v[148:149], v[40:41]
	v_pk_fma_f32 v[158:159], v[10:11], v[150:151], v[42:43]
	v_pk_fma_f32 v[152:153], v[12:13], v[120:121], v[152:153]
	v_pk_fma_f32 v[154:155], v[14:15], v[122:123], v[154:155]
	v_pk_fma_f32 v[156:157], v[16:17], v[124:125], v[156:157]
	v_pk_fma_f32 v[158:159], v[18:19], v[126:127], v[158:159]
	v_pk_fma_f32 v[152:153], v[20:21], v[128:129], v[152:153]
	v_pk_fma_f32 v[154:155], v[22:23], v[130:131], v[154:155]
	v_pk_fma_f32 v[156:157], v[24:25], v[132:133], v[156:157]
	v_pk_fma_f32 v[158:159], v[26:27], v[134:135], v[158:159]
	v_pk_fma_f32 v[152:153], v[28:29], v[136:137], v[152:153]
	v_pk_fma_f32 v[154:155], v[30:31], v[138:139], v[154:155]
	v_pk_fma_f32 v[156:157], v[32:33], v[140:141], v[156:157]
	v_pk_fma_f32 v[158:159], v[34:35], v[142:143], v[158:159]
	v_mul_f32_e32 v176, 0xbfb8aa3b, v152
	v_mul_f32_e32 v177, 0xbfb8aa3b, v153
	v_mul_f32_e32 v178, 0xbfb8aa3b, v154
	v_mul_f32_e32 v179, 0xbfb8aa3b, v155
	v_mul_f32_e32 v180, 0xbfb8aa3b, v156
	v_mul_f32_e32 v181, 0xbfb8aa3b, v157
	v_mul_f32_e32 v182, 0xbfb8aa3b, v158
	v_mul_f32_e32 v183, 0xbfb8aa3b, v159
	v_exp_f32_e32 v176, v176
	v_exp_f32_e32 v177, v177
	v_exp_f32_e32 v178, v178
	v_exp_f32_e32 v179, v179
	v_exp_f32_e32 v180, v180
	v_exp_f32_e32 v181, v181
	v_exp_f32_e32 v182, v182
	v_exp_f32_e32 v183, v183
	v_pk_add_f32 v[176:177], v[176:177], 1.0 op_sel_hi:[1,0]
	v_pk_add_f32 v[178:179], v[178:179], 1.0 op_sel_hi:[1,0]
	v_pk_add_f32 v[180:181], v[180:181], 1.0 op_sel_hi:[1,0]
	v_pk_add_f32 v[182:183], v[182:183], 1.0 op_sel_hi:[1,0]
	v_rcp_f32_e32 v176, v176
	v_rcp_f32_e32 v177, v177
	v_rcp_f32_e32 v178, v178
	v_rcp_f32_e32 v179, v179
	v_rcp_f32_e32 v180, v180
	v_rcp_f32_e32 v181, v181
	v_rcp_f32_e32 v182, v182
	v_rcp_f32_e32 v183, v183
	v_pk_mul_f32 v[152:153], v[152:153], v[176:177]
	v_pk_mul_f32 v[154:155], v[154:155], v[178:179]
	v_pk_mul_f32 v[156:157], v[156:157], v[180:181]
	v_pk_mul_f32 v[158:159], v[158:159], v[182:183]
	v_cvt_pk_bf16_f32 v176, v152, v153
	v_cvt_pk_bf16_f32 v177, v154, v155
	v_cvt_pk_bf16_f32 v178, v156, v157
	v_cvt_pk_bf16_f32 v179, v158, v159
	global_store_dwordx4 v2, v[176:179], s[48:49]
	s_add_u32 s48, s48, 0x4600
	s_addc_u32 s49, s49, 0
	s_waitcnt vmcnt(15)
; __device__ __forceinline__ unsigned pk2(float lo, float hi) { unsigned r; asm("v_cvt_pk_bf16_f32 %0, %1, %2" : "=v"(r) : "v"(lo), "v"(hi)); return r; }
; __device__ __forceinline__ float bflo(unsigned w) { return __uint_as_float(w << 16); }
; __device__ __forceinline__ float bfhi(unsigned w) { return __uint_as_float(w & 0xffff0000u); }
; __device__ __forceinline__ float siluf_(float x) { return x * __builtin_amdgcn_rcpf(1.f + __expf(-x)); }
; __device__ __forceinline__ void convbc_item(const Args& a, int layer, bool is_sample, int b, int cg32, int seq_row0, bf16_t* proj, const int tid) {
;     ...
;                 for (int i = 0; i < 8; ++i) o[i] = cb[i];
; #pragma unroll
;                 for (int k = 0; k < 4; ++k) { const u32x4 w = rw[t + k];
;                     o[0] += cw[k][0] * bflo(w.x); o[1] += cw[k][1] * bfhi(w.x); o[2] += cw[k][2] * bflo(w.y); o[3] += cw[k][3] * bfhi(w.y);
;                     o[4] += cw[k][4] * bflo(w.z); o[5] += cw[k][5] * bfhi(w.z); o[6] += cw[k][6] * bflo(w.w); o[7] += cw[k][7] * bfhi(w.w); }
;                 u32x4 w; w.x = pk2(siluf_(o[0]), siluf_(o[1])); w.y = pk2(siluf_(o[2]), siluf_(o[3])); w.z = pk2(siluf_(o[4]), siluf_(o[5])); w.w = pk2(siluf_(o[6]), siluf_(o[7]));
;                 *(u32x4*)(proj + (size_t)(seq_row0 + t0 + t) * PN + C_XBC + ch) = w;
;                 const int tl = t0 + t - (L - 3);
;                 if (tl >= 0) { const u32x4 rr = rw[t + 3]; float* q = nc + (size_t)tl * CONVC;
;                     *(f32x4*)q = (f32x4){bflo(rr.x), bfhi(rr.x), bflo(rr.y), bfhi(rr.y)}; *(f32x4*)(q + 4) = (f32x4){bflo(rr.z), bfhi(rr.z), bflo(rr.w), bfhi(rr.w)}; }
	v_lshlrev_b32_e32 v144, 16, v112
	v_and_b32_e32 v145, 0xffff0000, v112
	v_lshlrev_b32_e32 v146, 16, v113
	v_and_b32_e32 v147, 0xffff0000, v113
	v_lshlrev_b32_e32 v148, 16, v114
	v_and_b32_e32 v149, 0xffff0000, v114
	v_lshlrev_b32_e32 v150, 16, v115
	v_and_b32_e32 v151, 0xffff0000, v115
	v_pk_fma_f32 v[152:153], v[4:5], v[120:121], v[36:37]
	v_pk_fma_f32 v[154:155], v[6:7], v[122:123], v[38:39]
	v_pk_fma_f32 v[156:157], v[8:9], v[124:125], v[40:41]
	v_pk_fma_f32 v[158:159], v[10:11], v[126:127], v[42:43]
	v_pk_fma_f32 v[152:153], v[12:13], v[128:129], v[152:153]
	v_pk_fma_f32 v[154:155], v[14:15], v[130:131], v[154:155]
	v_pk_fma_f32 v[156:157], v[16:17], v[132:133], v[156:157]
	v_pk_fma_f32 v[158:159], v[18:19], v[134:135], v[158:159]
	v_pk_fma_f32 v[152:153], v[20:21], v[136:137], v[152:153]
	v_pk_fma_f32 v[154:155], v[22:23], v[138:139], v[154:155]
	v_pk_fma_f32 v[156:157], v[24:25], v[140:141], v[156:157]
	v_pk_fma_f32 v[158:159], v[26:27], v[142:143], v[158:159]
	v_pk_fma_f32 v[152:153], v[28:29], v[144:145], v[152:153]
	v_pk_fma_f32 v[154:155], v[30:31], v[146:147], v[154:155]
	v_pk_fma_f32 v[156:157], v[32:33], v[148:149], v[156:157]
	v_pk_fma_f32 v[158:159], v[34:35], v[150:151], v[158:159]
	v_mul_f32_e32 v176, 0xbfb8aa3b, v152
	v_mul_f32_e32 v177, 0xbfb8aa3b, v153
	v_mul_f32_e32 v178, 0xbfb8aa3b, v154
	v_mul_f32_e32 v179, 0xbfb8aa3b, v155
	v_mul_f32_e32 v180, 0xbfb8aa3b, v156
	v_mul_f32_e32 v181, 0xbfb8aa3b, v157
	v_mul_f32_e32 v182, 0xbfb8aa3b, v158
	v_mul_f32_e32 v183, 0xbfb8aa3b, v159
	v_exp_f32_e32 v176, v176
	v_exp_f32_e32 v177, v177
	v_exp_f32_e32 v178, v178
	v_exp_f32_e32 v179, v179
	v_exp_f32_e32 v180, v180
	v_exp_f32_e32 v181, v181
	v_exp_f32_e32 v182, v182
	v_exp_f32_e32 v183, v183
	v_pk_add_f32 v[176:177], v[176:177], 1.0 op_sel_hi:[1,0]
	v_pk_add_f32 v[178:179], v[178:179], 1.0 op_sel_hi:[1,0]
	v_pk_add_f32 v[180:181], v[180:181], 1.0 op_sel_hi:[1,0]
	v_pk_add_f32 v[182:183], v[182:183], 1.0 op_sel_hi:[1,0]
	v_rcp_f32_e32 v176, v176
	v_rcp_f32_e32 v177, v177
	v_rcp_f32_e32 v178, v178
	v_rcp_f32_e32 v179, v179
	v_rcp_f32_e32 v180, v180
	v_rcp_f32_e32 v181, v181
	v_rcp_f32_e32 v182, v182
	v_rcp_f32_e32 v183, v183
	v_pk_mul_f32 v[152:153], v[152:153], v[176:177]
	v_pk_mul_f32 v[154:155], v[154:155], v[178:179]
	v_pk_mul_f32 v[156:157], v[156:157], v[180:181]
	v_pk_mul_f32 v[158:159], v[158:159], v[182:183]
	v_cvt_pk_bf16_f32 v176, v152, v153
	v_cvt_pk_bf16_f32 v177, v154, v155
	v_cvt_pk_bf16_f32 v178, v156, v157
	v_cvt_pk_bf16_f32 v179, v158, v159
	global_store_dwordx4 v2, v[176:179], s[48:49]
	s_add_u32 s48, s48, 0x4600
	s_addc_u32 s49, s49, 0
	s_waitcnt vmcnt(15)
	v_lshlrev_b32_e32 v120, 16, v116
	v_and_b32_e32 v121, 0xffff0000, v116
	v_lshlrev_b32_e32 v122, 16, v117
	v_and_b32_e32 v123, 0xffff0000, v117
	v_lshlrev_b32_e32 v124, 16, v118
	v_and_b32_e32 v125, 0xffff0000, v118
	v_lshlrev_b32_e32 v126, 16, v119
	v_and_b32_e32 v127, 0xffff0000, v119
	v_pk_fma_f32 v[152:153], v[4:5], v[128:129], v[36:37]
	v_pk_fma_f32 v[154:155], v[6:7], v[130:131], v[38:39]
	v_pk_fma_f32 v[156:157], v[8:9], v[132:133], v[40:41]
	v_pk_fma_f32 v[158:159], v[10:11], v[134:135], v[42:43]
	v_pk_fma_f32 v[152:153], v[12:13], v[136:137], v[152:153]
	v_pk_fma_f32 v[154:155], v[14:15], v[138:139], v[154:155]
	v_pk_fma_f32 v[156:157], v[16:17], v[140:141], v[156:157]
	v_pk_fma_f32 v[158:159], v[18:19], v[142:143], v[158:159]
	v_pk_fma_f32 v[152:153], v[20:21], v[144:145], v[152:153]
	v_pk_fma_f32 v[154:155], v[22:23], v[146:147], v[154:155]
	v_pk_fma_f32 v[156:157], v[24:25], v[148:149], v[156:157]
	v_pk_fma_f32 v[158:159], v[26:27], v[150:151], v[158:159]
	v_pk_fma_f32 v[152:153], v[28:29], v[120:121], v[152:153]
	v_pk_fma_f32 v[154:155], v[30:31], v[122:123], v[154:155]
	v_pk_fma_f32 v[156:157], v[32:33], v[124:125], v[156:157]
	v_pk_fma_f32 v[158:159], v[34:35], v[126:127], v[158:159]
	v_mul_f32_e32 v176, 0xbfb8aa3b, v152
	v_mul_f32_e32 v177, 0xbfb8aa3b, v153
	v_mul_f32_e32 v178, 0xbfb8aa3b, v154
	v_mul_f32_e32 v179, 0xbfb8aa3b, v155
	v_mul_f32_e32 v180, 0xbfb8aa3b, v156
	v_mul_f32_e32 v181, 0xbfb8aa3b, v157
	v_mul_f32_e32 v182, 0xbfb8aa3b, v158
	v_mul_f32_e32 v183, 0xbfb8aa3b, v159
	v_exp_f32_e32 v176, v176
	v_exp_f32_e32 v177, v177
	v_exp_f32_e32 v178, v178
	v_exp_f32_e32 v179, v179
	v_exp_f32_e32 v180, v180
	v_exp_f32_e32 v181, v181
	v_exp_f32_e32 v182, v182
	v_exp_f32_e32 v183, v183
	v_pk_add_f32 v[176:177], v[176:177], 1.0 op_sel_hi:[1,0]
	v_pk_add_f32 v[178:179], v[178:179], 1.0 op_sel_hi:[1,0]
	v_pk_add_f32 v[180:181], v[180:181], 1.0 op_sel_hi:[1,0]
	v_pk_add_f32 v[182:183], v[182:183], 1.0 op_sel_hi:[1,0]
	v_rcp_f32_e32 v176, v176
	v_rcp_f32_e32 v177, v177
	v_rcp_f32_e32 v178, v178
	v_rcp_f32_e32 v179, v179
	v_rcp_f32_e32 v180, v180
	v_rcp_f32_e32 v181, v181
	v_rcp_f32_e32 v182, v182
	v_rcp_f32_e32 v183, v183
	v_pk_mul_f32 v[152:153], v[152:153], v[176:177]
	v_pk_mul_f32 v[154:155], v[154:155], v[178:179]
	v_pk_mul_f32 v[156:157], v[156:157], v[180:181]
	v_pk_mul_f32 v[158:159], v[158:159], v[182:183]
	v_cvt_pk_bf16_f32 v176, v152, v153
	v_cvt_pk_bf16_f32 v177, v154, v155
	v_cvt_pk_bf16_f32 v178, v156, v157
	v_cvt_pk_bf16_f32 v179, v158, v159
	global_store_dwordx4 v2, v[176:179], s[48:49]
	s_add_u32 s48, s48, 0x4600
	s_addc_u32 s49, s49, 0
	s_nop 1
	v_cmp_lt_u32_e32 vcc, 507, v166
	s_and_saveexec_b64 s[54:55], vcc
	global_store_dwordx4 v3, v[120:123], s[52:53]
	global_store_dwordx4 v3, v[124:127], s[52:53] offset:16
	s_mov_b64 exec, s[54:55]
	s_add_u32 s52, s52, 0x3000
	s_addc_u32 s53, s53, 0
	s_waitcnt vmcnt(17)
; __device__ __forceinline__ unsigned pk2(float lo, float hi) { unsigned r; asm("v_cvt_pk_bf16_f32 %0, %1, %2" : "=v"(r) : "v"(lo), "v"(hi)); return r; }
; __device__ __forceinline__ float bflo(unsigned w) { return __uint_as_float(w << 16); }
; __device__ __forceinline__ float bfhi(unsigned w) { return __uint_as_float(w & 0xffff0000u); }
; __device__ __forceinline__ float siluf_(float x) { return x * __builtin_amdgcn_rcpf(1.f + __expf(-x)); }
; __device__ __forceinline__ void convbc_item(const Args& a, int layer, bool is_sample, int b, int cg32, int seq_row0, bf16_t* proj, const int tid) {
;     ...
;                 for (int i = 0; i < 8; ++i) o[i] = cb[i];
; #pragma unroll
;                 for (int k = 0; k < 4; ++k) { const u32x4 w = rw[t + k];
;                     o[0] += cw[k][0] * bflo(w.x); o[1] += cw[k][1] * bfhi(w.x); o[2] += cw[k][2] * bflo(w.y); o[3] += cw[k][3] * bfhi(w.y);
;                     o[4] += cw[k][4] * bflo(w.z); o[5] += cw[k][5] * bfhi(w.z); o[6] += cw[k][6] * bflo(w.w); o[7] += cw[k][7] * bfhi(w.w); }
;                 u32x4 w; w.x = pk2(siluf_(o[0]), siluf_(o[1])); w.y = pk2(siluf_(o[2]), siluf_(o[3])); w.z = pk2(siluf_(o[4]), siluf_(o[5])); w.w = pk2(siluf_(o[6]), siluf_(o[7]));
;                 *(u32x4*)(proj + (size_t)(seq_row0 + t0 + t) * PN + C_XBC + ch) = w;
;                 const int tl = t0 + t - (L - 3);
;                 if (tl >= 0) { const u32x4 rr = rw[t + 3]; float* q = nc + (size_t)tl * CONVC;
;                     *(f32x4*)q = (f32x4){bflo(rr.x), bfhi(rr.x), bflo(rr.y), bfhi(rr.y)}; *(f32x4*)(q + 4) = (f32x4){bflo(rr.z), bfhi(rr.z), bflo(rr.w), bfhi(rr.w)}; }
	v_lshlrev_b32_e32 v128, 16, v184
	v_and_b32_e32 v129, 0xffff0000, v184
	v_lshlrev_b32_e32 v130, 16, v185
	v_and_b32_e32 v131, 0xffff0000, v185
	v_lshlrev_b32_e32 v132, 16, v186
	v_and_b32_e32 v133, 0xffff0000, v186
	v_lshlrev_b32_e32 v134, 16, v187
	v_and_b32_e32 v135, 0xffff0000, v187
	v_pk_fma_f32 v[152:153], v[4:5], v[136:137], v[36:37]
	v_pk_fma_f32 v[154:155], v[6:7], v[138:139], v[38:39]
	v_pk_fma_f32 v[156:157], v[8:9], v[140:141], v[40:41]
	v_pk_fma_f32 v[158:159], v[10:11], v[142:143], v[42:43]
	v_pk_fma_f32 v[152:153], v[12:13], v[144:145], v[152:153]
	v_pk_fma_f32 v[154:155], v[14:15], v[146:147], v[154:155]
	v_pk_fma_f32 v[156:157], v[16:17], v[148:149], v[156:157]
	v_pk_fma_f32 v[158:159], v[18:19], v[150:151], v[158:159]
	v_pk_fma_f32 v[152:153], v[20:21], v[120:121], v[152:153]
	v_pk_fma_f32 v[154:155], v[22:23], v[122:123], v[154:155]
	v_pk_fma_f32 v[156:157], v[24:25], v[124:125], v[156:157]
	v_pk_fma_f32 v[158:159], v[26:27], v[126:127], v[158:159]
	v_pk_fma_f32 v[152:153], v[28:29], v[128:129], v[152:153]
	v_pk_fma_f32 v[154:155], v[30:31], v[130:131], v[154:155]
	v_pk_fma_f32 v[156:157], v[32:33], v[132:133], v[156:157]
	v_pk_fma_f32 v[158:159], v[34:35], v[134:135], v[158:159]
	v_mul_f32_e32 v176, 0xbfb8aa3b, v152
	v_mul_f32_e32 v177, 0xbfb8aa3b, v153
	v_mul_f32_e32 v178, 0xbfb8aa3b, v154
	v_mul_f32_e32 v179, 0xbfb8aa3b, v155
	v_mul_f32_e32 v180, 0xbfb8aa3b, v156
	v_mul_f32_e32 v181, 0xbfb8aa3b, v157
	v_mul_f32_e32 v182, 0xbfb8aa3b, v158
	v_mul_f32_e32 v183, 0xbfb8aa3b, v159
	v_exp_f32_e32 v176, v176
	v_exp_f32_e32 v177, v177
	v_exp_f32_e32 v178, v178
	v_exp_f32_e32 v179, v179
	v_exp_f32_e32 v180, v180
	v_exp_f32_e32 v181, v181
	v_exp_f32_e32 v182, v182
	v_exp_f32_e32 v183, v183
	v_pk_add_f32 v[176:177], v[176:177], 1.0 op_sel_hi:[1,0]
	v_pk_add_f32 v[178:179], v[178:179], 1.0 op_sel_hi:[1,0]
	v_pk_add_f32 v[180:181], v[180:181], 1.0 op_sel_hi:[1,0]
	v_pk_add_f32 v[182:183], v[182:183], 1.0 op_sel_hi:[1,0]
	v_rcp_f32_e32 v176, v176
	v_rcp_f32_e32 v177, v177
	v_rcp_f32_e32 v178, v178
	v_rcp_f32_e32 v179, v179
	v_rcp_f32_e32 v180, v180
	v_rcp_f32_e32 v181, v181
	v_rcp_f32_e32 v182, v182
	v_rcp_f32_e32 v183, v183
	v_pk_mul_f32 v[152:153], v[152:153], v[176:177]
	v_pk_mul_f32 v[154:155], v[154:155], v[178:179]
	v_pk_mul_f32 v[156:157], v[156:157], v[180:181]
	v_pk_mul_f32 v[158:159], v[158:159], v[182:183]
	v_cvt_pk_bf16_f32 v176, v152, v153
	v_cvt_pk_bf16_f32 v177, v154, v155
	v_cvt_pk_bf16_f32 v178, v156, v157
	v_cvt_pk_bf16_f32 v179, v158, v159
	global_store_dwordx4 v2, v[176:179], s[48:49]
	s_add_u32 s48, s48, 0x4600
	s_addc_u32 s49, s49, 0
	s_nop 1
	v_cmp_lt_u32_e32 vcc, 507, v166
	s_and_saveexec_b64 s[54:55], vcc
	global_store_dwordx4 v3, v[128:131], s[52:53]
	global_store_dwordx4 v3, v[132:135], s[52:53] offset:16
	s_mov_b64 exec, s[54:55]
	s_add_u32 s52, s52, 0x3000
	s_addc_u32 s53, s53, 0
	s_waitcnt vmcnt(19)
	v_lshlrev_b32_e32 v136, 16, v188
	v_and_b32_e32 v137, 0xffff0000, v188
	v_lshlrev_b32_e32 v138, 16, v189
	v_and_b32_e32 v139, 0xffff0000, v189
	v_lshlrev_b32_e32 v140, 16, v190
	v_and_b32_e32 v141, 0xffff0000, v190
	v_lshlrev_b32_e32 v142, 16, v191
	v_and_b32_e32 v143, 0xffff0000, v191
	v_pk_fma_f32 v[152:153], v[4:5], v[144:145], v[36:37]
	v_pk_fma_f32 v[154:155], v[6:7], v[146:147], v[38:39]
	v_pk_fma_f32 v[156:157], v[8:9], v[148:149], v[40:41]
	v_pk_fma_f32 v[158:159], v[10:11], v[150:151], v[42:43]
	v_pk_fma_f32 v[152:153], v[12:13], v[120:121], v[152:153]
	v_pk_fma_f32 v[154:155], v[14:15], v[122:123], v[154:155]
	v_pk_fma_f32 v[156:157], v[16:17], v[124:125], v[156:157]
	v_pk_fma_f32 v[158:159], v[18:19], v[126:127], v[158:159]
	v_pk_fma_f32 v[152:153], v[20:21], v[128:129], v[152:153]
	v_pk_fma_f32 v[154:155], v[22:23], v[130:131], v[154:155]
	v_pk_fma_f32 v[156:157], v[24:25], v[132:133], v[156:157]
	v_pk_fma_f32 v[158:159], v[26:27], v[134:135], v[158:159]
	v_pk_fma_f32 v[152:153], v[28:29], v[136:137], v[152:153]
	v_pk_fma_f32 v[154:155], v[30:31], v[138:139], v[154:155]
	v_pk_fma_f32 v[156:157], v[32:33], v[140:141], v[156:157]
	v_pk_fma_f32 v[158:159], v[34:35], v[142:143], v[158:159]
	v_mul_f32_e32 v176, 0xbfb8aa3b, v152
	v_mul_f32_e32 v177, 0xbfb8aa3b, v153
	v_mul_f32_e32 v178, 0xbfb8aa3b, v154
	v_mul_f32_e32 v179, 0xbfb8aa3b, v155
	v_mul_f32_e32 v180, 0xbfb8aa3b, v156
	v_mul_f32_e32 v181, 0xbfb8aa3b, v157
	v_mul_f32_e32 v182, 0xbfb8aa3b, v158
	v_mul_f32_e32 v183, 0xbfb8aa3b, v159
	v_exp_f32_e32 v176, v176
	v_exp_f32_e32 v177, v177
	v_exp_f32_e32 v178, v178
	v_exp_f32_e32 v179, v179
	v_exp_f32_e32 v180, v180
	v_exp_f32_e32 v181, v181
	v_exp_f32_e32 v182, v182
	v_exp_f32_e32 v183, v183
	v_pk_add_f32 v[176:177], v[176:177], 1.0 op_sel_hi:[1,0]
	v_pk_add_f32 v[178:179], v[178:179], 1.0 op_sel_hi:[1,0]
	v_pk_add_f32 v[180:181], v[180:181], 1.0 op_sel_hi:[1,0]
	v_pk_add_f32 v[182:183], v[182:183], 1.0 op_sel_hi:[1,0]
	v_rcp_f32_e32 v176, v176
	v_rcp_f32_e32 v177, v177
	v_rcp_f32_e32 v178, v178
	v_rcp_f32_e32 v179, v179
	v_rcp_f32_e32 v180, v180
	v_rcp_f32_e32 v181, v181
	v_rcp_f32_e32 v182, v182
	v_rcp_f32_e32 v183, v183
	v_pk_mul_f32 v[152:153], v[152:153], v[176:177]
	v_pk_mul_f32 v[154:155], v[154:155], v[178:179]
	v_pk_mul_f32 v[156:157], v[156:157], v[180:181]
	v_pk_mul_f32 v[158:159], v[158:159], v[182:183]
	v_cvt_pk_bf16_f32 v176, v152, v153
	v_cvt_pk_bf16_f32 v177, v154, v155
	v_cvt_pk_bf16_f32 v178, v156, v157
	v_cvt_pk_bf16_f32 v179, v158, v159
	global_store_dwordx4 v2, v[176:179], s[48:49]
	s_add_u32 s48, s48, 0x4600
	s_addc_u32 s49, s49, 0
	s_nop 1
	v_cmp_lt_u32_e32 vcc, 507, v166
	s_and_saveexec_b64 s[54:55], vcc
	global_store_dwordx4 v3, v[136:139], s[52:53]
	global_store_dwordx4 v3, v[140:143], s[52:53] offset:16
	s_mov_b64 exec, s[54:55]
	s_nop 1
	s_mov_b64 s[4:5], 0
